# v63 + loop-edge edit: priority stays raised across both MFMA groups of an inproj1 k-step (redundant setprio 0/1 pair removed)
# speedup vs baseline: 1.0038x; 1.0003x over previous
.LBB0_569:
	s_add_i32 s5, s1, 0x8000
	s_and_b32 s13, s5, 0x8000
	s_add_u32 s13, s13, s38
	s_and_b32 s1, s1, 0x8000
	s_add_i32 s1, s1, 0
	v_add_u32_e32 v81, s1, v75
	v_add_u32_e32 v94, v81, v76
	v_add_u32_e32 v81, v81, v77
	s_add_u32 m0, s13, 0
	ds_read_b128 v[82:85], v94
	global_load_lds_dwordx4 v242, s[34:35]
	ds_read_b128 v[86:89], v94 offset:2048
	s_add_u32 m0, s13, 4096
	ds_read_b128 v[90:93], v94 offset:4096
	global_load_lds_dwordx4 v243, s[34:35]
	ds_read_b128 v[100:103], v94 offset:6144
	s_add_u32 m0, s13, 8192
	ds_read_b128 v[104:107], v81 offset:16384
	global_load_lds_dwordx4 v244, s[34:35]
	ds_read_b128 v[108:111], v81 offset:18432
	s_add_u32 m0, s13, 12288
	ds_read_b128 v[112:115], v81 offset:20480
	global_load_lds_dwordx4 v245, s[34:35]
	ds_read_b128 v[116:119], v81 offset:22528
	v_add_u32_e32 v206, s1, v78
	v_add_u32_e32 v207, v206, v76
	v_add_u32_e32 v208, v206, v77
	s_add_u32 m0, s13, 16384
	ds_read_b128 v[210:213], v207
	global_load_lds_dwordx4 v242, s[36:37]
	ds_read_b128 v[214:217], v207 offset:2048
	s_add_u32 m0, s13, 20480
	ds_read_b128 v[218:221], v207 offset:4096
	global_load_lds_dwordx4 v243, s[36:37]
	ds_read_b128 v[222:225], v207 offset:6144
	s_add_u32 m0, s13, 24576
	ds_read_b128 v[226:229], v208 offset:16384
	global_load_lds_dwordx4 v244, s[36:37]
	ds_read_b128 v[230:233], v208 offset:18432
	s_add_u32 m0, s13, 28672
	ds_read_b128 v[234:237], v208 offset:20480
	global_load_lds_dwordx4 v245, s[36:37]
	ds_read_b128 v[238:241], v208 offset:22528
	s_add_u32 s34, s34, 0x80
	s_addc_u32 s35, s35, 0
	s_add_u32 s36, s36, 0x80
	s_addc_u32 s37, s37, 0
	s_setprio 1
	s_waitcnt lgkmcnt(8)
	v_mfma_f32_16x16x32_bf16 v[60:63], v[104:107], v[82:85], v[60:63]
	v_mfma_f32_16x16x32_bf16 v[56:59], v[108:111], v[82:85], v[56:59]
	v_mfma_f32_16x16x32_bf16 v[52:55], v[112:115], v[82:85], v[52:55]
	v_mfma_f32_16x16x32_bf16 v[48:51], v[116:119], v[82:85], v[48:51]
	v_mfma_f32_16x16x32_bf16 v[44:47], v[104:107], v[86:89], v[44:47]
	v_mfma_f32_16x16x32_bf16 v[40:43], v[108:111], v[86:89], v[40:43]
	v_mfma_f32_16x16x32_bf16 v[36:39], v[112:115], v[86:89], v[36:39]
	v_mfma_f32_16x16x32_bf16 v[32:35], v[116:119], v[86:89], v[32:35]
	v_mfma_f32_16x16x32_bf16 v[28:31], v[104:107], v[90:93], v[28:31]
	v_mfma_f32_16x16x32_bf16 v[24:27], v[108:111], v[90:93], v[24:27]
	v_mfma_f32_16x16x32_bf16 v[20:23], v[112:115], v[90:93], v[20:23]
	v_mfma_f32_16x16x32_bf16 v[16:19], v[116:119], v[90:93], v[16:19]
	v_mfma_f32_16x16x32_bf16 v[12:15], v[104:107], v[100:103], v[12:15]
	v_mfma_f32_16x16x32_bf16 v[8:11], v[108:111], v[100:103], v[8:11]
	v_mfma_f32_16x16x32_bf16 v[4:7], v[112:115], v[100:103], v[4:7]
	v_mfma_f32_16x16x32_bf16 v[0:3], v[116:119], v[100:103], v[0:3]
	s_waitcnt lgkmcnt(0)
	v_mfma_f32_16x16x32_bf16 v[60:63], v[226:229], v[210:213], v[60:63]
	v_mfma_f32_16x16x32_bf16 v[56:59], v[230:233], v[210:213], v[56:59]
	v_mfma_f32_16x16x32_bf16 v[52:55], v[234:237], v[210:213], v[52:55]
	v_mfma_f32_16x16x32_bf16 v[48:51], v[238:241], v[210:213], v[48:51]
	v_mfma_f32_16x16x32_bf16 v[44:47], v[226:229], v[214:217], v[44:47]
	v_mfma_f32_16x16x32_bf16 v[40:43], v[230:233], v[214:217], v[40:43]
	v_mfma_f32_16x16x32_bf16 v[36:39], v[234:237], v[214:217], v[36:39]
	v_mfma_f32_16x16x32_bf16 v[32:35], v[238:241], v[214:217], v[32:35]
	v_mfma_f32_16x16x32_bf16 v[28:31], v[226:229], v[218:221], v[28:31]
	v_mfma_f32_16x16x32_bf16 v[24:27], v[230:233], v[218:221], v[24:27]
	v_mfma_f32_16x16x32_bf16 v[20:23], v[234:237], v[218:221], v[20:23]
	v_mfma_f32_16x16x32_bf16 v[16:19], v[238:241], v[218:221], v[16:19]
	v_mfma_f32_16x16x32_bf16 v[12:15], v[226:229], v[222:225], v[12:15]
	v_mfma_f32_16x16x32_bf16 v[8:11], v[230:233], v[222:225], v[8:11]
	v_mfma_f32_16x16x32_bf16 v[4:7], v[234:237], v[222:225], v[4:7]
	v_mfma_f32_16x16x32_bf16 v[0:3], v[238:241], v[222:225], v[0:3]
	s_setprio 0
	s_waitcnt vmcnt(0)
	s_add_u32 s6, s6, 0x80
	s_addc_u32 s7, s7, 0
	s_cmpk_lg_i32 s6, 0x780
	s_mov_b32 s1, s5
	s_waitcnt vmcnt(0)
	s_barrier
	s_cbranch_scc1 .LBB0_569
	v_add_u32_e32 v81, v79, v77
	ds_read_b128 v[70:73], v81 offset:55296
	ds_read_b128 v[82:85], v81 offset:53248
	ds_read_b128 v[86:89], v81 offset:51200
	ds_read_b128 v[90:93], v81 offset:49152
	v_add_u32_e32 v81, v79, v76
	ds_read_b128 v[100:103], v81 offset:38912
	ds_read_b128 v[104:107], v81 offset:36864
	ds_read_b128 v[108:111], v81 offset:34816
	ds_read_b128 v[112:115], v81 offset:32768
	s_setprio 1
	s_waitcnt lgkmcnt(0)
	v_mfma_f32_16x16x32_bf16 v[60:63], v[90:93], v[112:115], v[60:63]
	v_mfma_f32_16x16x32_bf16 v[56:59], v[86:89], v[112:115], v[56:59]
	v_mfma_f32_16x16x32_bf16 v[52:55], v[82:85], v[112:115], v[52:55]
	v_mfma_f32_16x16x32_bf16 v[48:51], v[70:73], v[112:115], v[48:51]
	v_mfma_f32_16x16x32_bf16 v[44:47], v[90:93], v[108:111], v[44:47]
	v_mfma_f32_16x16x32_bf16 v[40:43], v[86:89], v[108:111], v[40:43]
	v_mfma_f32_16x16x32_bf16 v[36:39], v[82:85], v[108:111], v[36:39]
	v_mfma_f32_16x16x32_bf16 v[32:35], v[70:73], v[108:111], v[32:35]
	v_mfma_f32_16x16x32_bf16 v[28:31], v[90:93], v[104:107], v[28:31]
	v_mfma_f32_16x16x32_bf16 v[24:27], v[86:89], v[104:107], v[24:27]
	v_mfma_f32_16x16x32_bf16 v[20:23], v[82:85], v[104:107], v[20:23]
	v_mfma_f32_16x16x32_bf16 v[16:19], v[70:73], v[104:107], v[16:19]
	v_mfma_f32_16x16x32_bf16 v[12:15], v[90:93], v[100:103], v[12:15]
	v_mfma_f32_16x16x32_bf16 v[8:11], v[86:89], v[100:103], v[8:11]
	v_mfma_f32_16x16x32_bf16 v[4:7], v[82:85], v[100:103], v[4:7]
	v_mfma_f32_16x16x32_bf16 v[0:3], v[70:73], v[100:103], v[0:3]
	s_setprio 0
	v_add_u32_e32 v81, v80, v76
	ds_read_b128 v[70:73], v81 offset:32768
	ds_read_b128 v[82:85], v81 offset:34816
	ds_read_b128 v[86:89], v81 offset:36864
	ds_read_b128 v[90:93], v81 offset:38912
	v_add_u32_e32 v81, v80, v77
	ds_read_b128 v[100:103], v81 offset:49152
	ds_read_b128 v[104:107], v81 offset:51200
	ds_read_b128 v[108:111], v81 offset:53248
	ds_read_b128 v[112:115], v81 offset:55296
	s_setprio 1
	s_waitcnt lgkmcnt(3)
	v_mfma_f32_16x16x32_bf16 v[60:63], v[100:103], v[70:73], v[60:63]
	s_waitcnt lgkmcnt(2)
	v_mfma_f32_16x16x32_bf16 v[56:59], v[104:107], v[70:73], v[56:59]
	s_waitcnt lgkmcnt(1)
	v_mfma_f32_16x16x32_bf16 v[52:55], v[108:111], v[70:73], v[52:55]
	s_waitcnt lgkmcnt(0)
	v_mfma_f32_16x16x32_bf16 v[48:51], v[112:115], v[70:73], v[48:51]
	v_mfma_f32_16x16x32_bf16 v[44:47], v[100:103], v[82:85], v[44:47]
	v_mfma_f32_16x16x32_bf16 v[40:43], v[104:107], v[82:85], v[40:43]
	v_mfma_f32_16x16x32_bf16 v[36:39], v[108:111], v[82:85], v[36:39]
	v_mfma_f32_16x16x32_bf16 v[32:35], v[112:115], v[82:85], v[32:35]
	v_mfma_f32_16x16x32_bf16 v[28:31], v[100:103], v[86:89], v[28:31]
	v_mfma_f32_16x16x32_bf16 v[24:27], v[104:107], v[86:89], v[24:27]
	v_mfma_f32_16x16x32_bf16 v[20:23], v[108:111], v[86:89], v[20:23]
	v_mfma_f32_16x16x32_bf16 v[16:19], v[112:115], v[86:89], v[16:19]
	v_mfma_f32_16x16x32_bf16 v[12:15], v[100:103], v[90:93], v[12:15]
	v_mfma_f32_16x16x32_bf16 v[8:11], v[104:107], v[90:93], v[8:11]
	v_mfma_f32_16x16x32_bf16 v[4:7], v[108:111], v[90:93], v[4:7]
	v_mfma_f32_16x16x32_bf16 v[0:3], v[112:115], v[90:93], v[0:3]
	s_setprio 0
	v_mov_b32_e32 v70, v97
	s_waitcnt vmcnt(0)
	s_barrier
	s_lshl_b32 s0, s0, 7
	v_add_u32_e32 v70, v70, v176
	v_and_b32_e32 v71, 64, v70
	v_ashrrev_i32_e32 v72, 1, v70
	v_lshrrev_b32_e32 v73, 2, v70
	v_and_or_b32 v70, v70, 15, s0
	s_lshl_b32 s0, s4, 7
	s_ashr_i32 s1, s0, 31
	s_lshl_b64 s[0:1], s[0:1], 1
	s_mov_b32 s6, 0
	v_and_b32_e32 v72, 0xffffffc0, v72
	s_add_u32 s0, s2, s0
	v_and_or_b32 v81, v73, 12, v71
	v_add_u32_e32 v82, v70, v72
	s_addc_u32 s1, s8, s1
	v_lshlrev_b32_e32 v96, 1, v81
	v_and_b32_sdwa v81, v62, v154 dst_sel:DWORD dst_unused:UNUSED_PAD src0_sel:WORD_1 src1_sel:DWORD
	v_and_b32_sdwa v83, v60, v154 dst_sel:DWORD dst_unused:UNUSED_PAD src0_sel:WORD_1 src1_sel:DWORD
	v_add3_u32 v60, v60, v83, s33
	v_add3_u32 v62, v62, v81, s33
	v_and_b32_sdwa v81, v63, v154 dst_sel:DWORD dst_unused:UNUSED_PAD src0_sel:WORD_1 src1_sel:DWORD
	v_and_b32_sdwa v83, v61, v154 dst_sel:DWORD dst_unused:UNUSED_PAD src0_sel:WORD_1 src1_sel:DWORD
	v_mov_b64_e32 v[70:71], s[0:1]
	s_movk_i32 s4, 0x3200
	v_add3_u32 v63, v63, v81, s33
	v_add3_u32 v61, v61, v83, s33
	v_mad_i64_i32 v[72:73], s[0:1], v82, s4, v[70:71]
	v_and_b32_e32 v63, 0xffff0000, v63
	v_and_b32_e32 v81, 0xffff0000, v61
	v_lshl_add_u64 v[72:73], v[72:73], 0, v[96:97]
	v_or_b32_sdwa v61, v63, v62 dst_sel:DWORD dst_unused:UNUSED_PAD src0_sel:DWORD src1_sel:WORD_1
	v_or_b32_sdwa v60, v81, v60 dst_sel:DWORD dst_unused:UNUSED_PAD src0_sel:DWORD src1_sel:WORD_1
	global_store_dwordx2 v[72:73], v[60:61], off
	v_and_b32_sdwa v60, v58, v154 dst_sel:DWORD dst_unused:UNUSED_PAD src0_sel:WORD_1 src1_sel:DWORD
	v_and_b32_sdwa v61, v56, v154 dst_sel:DWORD dst_unused:UNUSED_PAD src0_sel:WORD_1 src1_sel:DWORD
	v_add3_u32 v56, v56, v61, s33
	v_add3_u32 v58, v58, v60, s33
	v_and_b32_sdwa v60, v59, v154 dst_sel:DWORD dst_unused:UNUSED_PAD src0_sel:WORD_1 src1_sel:DWORD
	v_and_b32_sdwa v61, v57, v154 dst_sel:DWORD dst_unused:UNUSED_PAD src0_sel:WORD_1 src1_sel:DWORD
	v_add3_u32 v59, v59, v60, s33
	v_add3_u32 v57, v57, v61, s33
	v_and_b32_e32 v59, 0xffff0000, v59
	v_and_b32_e32 v60, 0xffff0000, v57
	v_or_b32_sdwa v57, v59, v58 dst_sel:DWORD dst_unused:UNUSED_PAD src0_sel:DWORD src1_sel:WORD_1
	v_or_b32_sdwa v56, v60, v56 dst_sel:DWORD dst_unused:UNUSED_PAD src0_sel:DWORD src1_sel:WORD_1
	global_store_dwordx2 v[72:73], v[56:57], off offset:32
	v_and_b32_sdwa v56, v54, v154 dst_sel:DWORD dst_unused:UNUSED_PAD src0_sel:WORD_1 src1_sel:DWORD
	v_and_b32_sdwa v57, v52, v154 dst_sel:DWORD dst_unused:UNUSED_PAD src0_sel:WORD_1 src1_sel:DWORD
	v_add3_u32 v52, v52, v57, s33
	v_add3_u32 v54, v54, v56, s33
	v_and_b32_sdwa v56, v55, v154 dst_sel:DWORD dst_unused:UNUSED_PAD src0_sel:WORD_1 src1_sel:DWORD
	v_and_b32_sdwa v57, v53, v154 dst_sel:DWORD dst_unused:UNUSED_PAD src0_sel:WORD_1 src1_sel:DWORD
	v_add3_u32 v55, v55, v56, s33
	v_add3_u32 v53, v53, v57, s33
	v_and_b32_e32 v55, 0xffff0000, v55
	v_and_b32_e32 v56, 0xffff0000, v53
	v_or_b32_sdwa v53, v55, v54 dst_sel:DWORD dst_unused:UNUSED_PAD src0_sel:DWORD src1_sel:WORD_1
	v_or_b32_sdwa v52, v56, v52 dst_sel:DWORD dst_unused:UNUSED_PAD src0_sel:DWORD src1_sel:WORD_1
	global_store_dwordx2 v[72:73], v[52:53], off offset:64
	v_and_b32_sdwa v52, v50, v154 dst_sel:DWORD dst_unused:UNUSED_PAD src0_sel:WORD_1 src1_sel:DWORD
	v_and_b32_sdwa v53, v48, v154 dst_sel:DWORD dst_unused:UNUSED_PAD src0_sel:WORD_1 src1_sel:DWORD
	v_add3_u32 v48, v48, v53, s33
	v_add3_u32 v50, v50, v52, s33
	v_and_b32_sdwa v52, v51, v154 dst_sel:DWORD dst_unused:UNUSED_PAD src0_sel:WORD_1 src1_sel:DWORD
	v_and_b32_sdwa v53, v49, v154 dst_sel:DWORD dst_unused:UNUSED_PAD src0_sel:WORD_1 src1_sel:DWORD
	v_add3_u32 v51, v51, v52, s33
	v_add3_u32 v49, v49, v53, s33
	v_and_b32_e32 v51, 0xffff0000, v51
	v_and_b32_e32 v52, 0xffff0000, v49
	v_or_b32_sdwa v49, v51, v50 dst_sel:DWORD dst_unused:UNUSED_PAD src0_sel:DWORD src1_sel:WORD_1
	v_or_b32_sdwa v48, v52, v48 dst_sel:DWORD dst_unused:UNUSED_PAD src0_sel:DWORD src1_sel:WORD_1
	global_store_dwordx2 v[72:73], v[48:49], off offset:96
	v_and_b32_sdwa v50, v46, v154 dst_sel:DWORD dst_unused:UNUSED_PAD src0_sel:WORD_1 src1_sel:DWORD
	v_and_b32_sdwa v51, v44, v154 dst_sel:DWORD dst_unused:UNUSED_PAD src0_sel:WORD_1 src1_sel:DWORD
	v_add3_u32 v44, v44, v51, s33
	v_add3_u32 v46, v46, v50, s33
	v_and_b32_sdwa v50, v47, v154 dst_sel:DWORD dst_unused:UNUSED_PAD src0_sel:WORD_1 src1_sel:DWORD
	v_and_b32_sdwa v51, v45, v154 dst_sel:DWORD dst_unused:UNUSED_PAD src0_sel:WORD_1 src1_sel:DWORD
	v_or_b32_e32 v48, 16, v82
	v_add3_u32 v47, v47, v50, s33
	v_add3_u32 v45, v45, v51, s33
	v_mad_i64_i32 v[48:49], s[0:1], v48, s4, v[70:71]
	v_and_b32_e32 v47, 0xffff0000, v47
	v_and_b32_e32 v50, 0xffff0000, v45
	v_lshl_add_u64 v[48:49], v[48:49], 0, v[96:97]
	v_or_b32_sdwa v45, v47, v46 dst_sel:DWORD dst_unused:UNUSED_PAD src0_sel:DWORD src1_sel:WORD_1
	v_or_b32_sdwa v44, v50, v44 dst_sel:DWORD dst_unused:UNUSED_PAD src0_sel:DWORD src1_sel:WORD_1
	global_store_dwordx2 v[48:49], v[44:45], off
	v_and_b32_sdwa v44, v42, v154 dst_sel:DWORD dst_unused:UNUSED_PAD src0_sel:WORD_1 src1_sel:DWORD
	v_and_b32_sdwa v45, v40, v154 dst_sel:DWORD dst_unused:UNUSED_PAD src0_sel:WORD_1 src1_sel:DWORD
	v_add3_u32 v40, v40, v45, s33
	v_add3_u32 v42, v42, v44, s33
	v_and_b32_sdwa v44, v43, v154 dst_sel:DWORD dst_unused:UNUSED_PAD src0_sel:WORD_1 src1_sel:DWORD
	v_and_b32_sdwa v45, v41, v154 dst_sel:DWORD dst_unused:UNUSED_PAD src0_sel:WORD_1 src1_sel:DWORD
	v_add3_u32 v43, v43, v44, s33
	v_add3_u32 v41, v41, v45, s33
	v_and_b32_e32 v43, 0xffff0000, v43
	v_and_b32_e32 v44, 0xffff0000, v41
	v_or_b32_sdwa v41, v43, v42 dst_sel:DWORD dst_unused:UNUSED_PAD src0_sel:DWORD src1_sel:WORD_1
	v_or_b32_sdwa v40, v44, v40 dst_sel:DWORD dst_unused:UNUSED_PAD src0_sel:DWORD src1_sel:WORD_1
	global_store_dwordx2 v[48:49], v[40:41], off offset:32
	v_and_b32_sdwa v40, v38, v154 dst_sel:DWORD dst_unused:UNUSED_PAD src0_sel:WORD_1 src1_sel:DWORD
	v_and_b32_sdwa v41, v36, v154 dst_sel:DWORD dst_unused:UNUSED_PAD src0_sel:WORD_1 src1_sel:DWORD
	v_add3_u32 v36, v36, v41, s33
	v_add3_u32 v38, v38, v40, s33
	v_and_b32_sdwa v40, v39, v154 dst_sel:DWORD dst_unused:UNUSED_PAD src0_sel:WORD_1 src1_sel:DWORD
	v_and_b32_sdwa v41, v37, v154 dst_sel:DWORD dst_unused:UNUSED_PAD src0_sel:WORD_1 src1_sel:DWORD
	v_add3_u32 v39, v39, v40, s33
	v_add3_u32 v37, v37, v41, s33
	v_and_b32_e32 v39, 0xffff0000, v39
	v_and_b32_e32 v40, 0xffff0000, v37
	v_or_b32_sdwa v37, v39, v38 dst_sel:DWORD dst_unused:UNUSED_PAD src0_sel:DWORD src1_sel:WORD_1
	v_or_b32_sdwa v36, v40, v36 dst_sel:DWORD dst_unused:UNUSED_PAD src0_sel:DWORD src1_sel:WORD_1
	global_store_dwordx2 v[48:49], v[36:37], off offset:64
	v_and_b32_sdwa v36, v34, v154 dst_sel:DWORD dst_unused:UNUSED_PAD src0_sel:WORD_1 src1_sel:DWORD
	v_and_b32_sdwa v37, v32, v154 dst_sel:DWORD dst_unused:UNUSED_PAD src0_sel:WORD_1 src1_sel:DWORD
	v_add3_u32 v32, v32, v37, s33
	v_add3_u32 v34, v34, v36, s33
	v_and_b32_sdwa v36, v35, v154 dst_sel:DWORD dst_unused:UNUSED_PAD src0_sel:WORD_1 src1_sel:DWORD
	v_and_b32_sdwa v37, v33, v154 dst_sel:DWORD dst_unused:UNUSED_PAD src0_sel:WORD_1 src1_sel:DWORD
	v_add3_u32 v35, v35, v36, s33
	v_add3_u32 v33, v33, v37, s33
	v_and_b32_e32 v35, 0xffff0000, v35
	v_and_b32_e32 v36, 0xffff0000, v33
	v_or_b32_sdwa v33, v35, v34 dst_sel:DWORD dst_unused:UNUSED_PAD src0_sel:DWORD src1_sel:WORD_1
	v_or_b32_sdwa v32, v36, v32 dst_sel:DWORD dst_unused:UNUSED_PAD src0_sel:DWORD src1_sel:WORD_1
	global_store_dwordx2 v[48:49], v[32:33], off offset:96
	v_and_b32_sdwa v34, v30, v154 dst_sel:DWORD dst_unused:UNUSED_PAD src0_sel:WORD_1 src1_sel:DWORD
	v_and_b32_sdwa v35, v28, v154 dst_sel:DWORD dst_unused:UNUSED_PAD src0_sel:WORD_1 src1_sel:DWORD
	v_add3_u32 v28, v28, v35, s33
	v_add3_u32 v30, v30, v34, s33
	v_and_b32_sdwa v34, v31, v154 dst_sel:DWORD dst_unused:UNUSED_PAD src0_sel:WORD_1 src1_sel:DWORD
	v_and_b32_sdwa v35, v29, v154 dst_sel:DWORD dst_unused:UNUSED_PAD src0_sel:WORD_1 src1_sel:DWORD
	v_or_b32_e32 v32, 32, v82
	v_add3_u32 v31, v31, v34, s33
	v_add3_u32 v29, v29, v35, s33
	v_mad_i64_i32 v[32:33], s[0:1], v32, s4, v[70:71]
	v_and_b32_e32 v31, 0xffff0000, v31
	v_and_b32_e32 v34, 0xffff0000, v29
	v_lshl_add_u64 v[32:33], v[32:33], 0, v[96:97]
	v_or_b32_sdwa v29, v31, v30 dst_sel:DWORD dst_unused:UNUSED_PAD src0_sel:DWORD src1_sel:WORD_1
	v_or_b32_sdwa v28, v34, v28 dst_sel:DWORD dst_unused:UNUSED_PAD src0_sel:DWORD src1_sel:WORD_1
	global_store_dwordx2 v[32:33], v[28:29], off
	v_and_b32_sdwa v28, v26, v154 dst_sel:DWORD dst_unused:UNUSED_PAD src0_sel:WORD_1 src1_sel:DWORD
	v_and_b32_sdwa v29, v24, v154 dst_sel:DWORD dst_unused:UNUSED_PAD src0_sel:WORD_1 src1_sel:DWORD
	v_add3_u32 v24, v24, v29, s33
	v_add3_u32 v26, v26, v28, s33
	v_and_b32_sdwa v28, v27, v154 dst_sel:DWORD dst_unused:UNUSED_PAD src0_sel:WORD_1 src1_sel:DWORD
	v_and_b32_sdwa v29, v25, v154 dst_sel:DWORD dst_unused:UNUSED_PAD src0_sel:WORD_1 src1_sel:DWORD
	v_add3_u32 v27, v27, v28, s33
	v_add3_u32 v25, v25, v29, s33
	v_and_b32_e32 v27, 0xffff0000, v27
	v_and_b32_e32 v28, 0xffff0000, v25
	v_or_b32_sdwa v25, v27, v26 dst_sel:DWORD dst_unused:UNUSED_PAD src0_sel:DWORD src1_sel:WORD_1
	v_or_b32_sdwa v24, v28, v24 dst_sel:DWORD dst_unused:UNUSED_PAD src0_sel:DWORD src1_sel:WORD_1
	global_store_dwordx2 v[32:33], v[24:25], off offset:32
	v_and_b32_sdwa v24, v22, v154 dst_sel:DWORD dst_unused:UNUSED_PAD src0_sel:WORD_1 src1_sel:DWORD
	v_and_b32_sdwa v25, v20, v154 dst_sel:DWORD dst_unused:UNUSED_PAD src0_sel:WORD_1 src1_sel:DWORD
	v_add3_u32 v20, v20, v25, s33
	v_add3_u32 v22, v22, v24, s33
	v_and_b32_sdwa v24, v23, v154 dst_sel:DWORD dst_unused:UNUSED_PAD src0_sel:WORD_1 src1_sel:DWORD
	v_and_b32_sdwa v25, v21, v154 dst_sel:DWORD dst_unused:UNUSED_PAD src0_sel:WORD_1 src1_sel:DWORD
	v_add3_u32 v23, v23, v24, s33
	v_add3_u32 v21, v21, v25, s33
	v_and_b32_e32 v23, 0xffff0000, v23
	v_and_b32_e32 v24, 0xffff0000, v21
	v_or_b32_sdwa v21, v23, v22 dst_sel:DWORD dst_unused:UNUSED_PAD src0_sel:DWORD src1_sel:WORD_1
	v_or_b32_sdwa v20, v24, v20 dst_sel:DWORD dst_unused:UNUSED_PAD src0_sel:DWORD src1_sel:WORD_1
	global_store_dwordx2 v[32:33], v[20:21], off offset:64
	v_and_b32_sdwa v20, v18, v154 dst_sel:DWORD dst_unused:UNUSED_PAD src0_sel:WORD_1 src1_sel:DWORD
	v_and_b32_sdwa v21, v16, v154 dst_sel:DWORD dst_unused:UNUSED_PAD src0_sel:WORD_1 src1_sel:DWORD
	v_add3_u32 v16, v16, v21, s33
	v_add3_u32 v18, v18, v20, s33
	v_and_b32_sdwa v20, v19, v154 dst_sel:DWORD dst_unused:UNUSED_PAD src0_sel:WORD_1 src1_sel:DWORD
	v_and_b32_sdwa v21, v17, v154 dst_sel:DWORD dst_unused:UNUSED_PAD src0_sel:WORD_1 src1_sel:DWORD
	v_add3_u32 v19, v19, v20, s33
	v_add3_u32 v17, v17, v21, s33
	v_and_b32_e32 v19, 0xffff0000, v19
	v_and_b32_e32 v20, 0xffff0000, v17
	v_or_b32_sdwa v17, v19, v18 dst_sel:DWORD dst_unused:UNUSED_PAD src0_sel:DWORD src1_sel:WORD_1
	v_or_b32_sdwa v16, v20, v16 dst_sel:DWORD dst_unused:UNUSED_PAD src0_sel:DWORD src1_sel:WORD_1
	global_store_dwordx2 v[32:33], v[16:17], off offset:96
	v_and_b32_sdwa v18, v14, v154 dst_sel:DWORD dst_unused:UNUSED_PAD src0_sel:WORD_1 src1_sel:DWORD
	v_and_b32_sdwa v19, v12, v154 dst_sel:DWORD dst_unused:UNUSED_PAD src0_sel:WORD_1 src1_sel:DWORD
	v_add3_u32 v12, v12, v19, s33
	v_add3_u32 v14, v14, v18, s33
	v_and_b32_sdwa v18, v15, v154 dst_sel:DWORD dst_unused:UNUSED_PAD src0_sel:WORD_1 src1_sel:DWORD
	v_and_b32_sdwa v19, v13, v154 dst_sel:DWORD dst_unused:UNUSED_PAD src0_sel:WORD_1 src1_sel:DWORD
	v_or_b32_e32 v16, 48, v82
	v_add3_u32 v15, v15, v18, s33
	v_add3_u32 v13, v13, v19, s33
	v_mad_i64_i32 v[16:17], s[0:1], v16, s4, v[70:71]
	v_and_b32_e32 v15, 0xffff0000, v15
	v_and_b32_e32 v18, 0xffff0000, v13
	v_lshl_add_u64 v[16:17], v[16:17], 0, v[96:97]
	v_or_b32_sdwa v13, v15, v14 dst_sel:DWORD dst_unused:UNUSED_PAD src0_sel:DWORD src1_sel:WORD_1
	v_or_b32_sdwa v12, v18, v12 dst_sel:DWORD dst_unused:UNUSED_PAD src0_sel:DWORD src1_sel:WORD_1
	global_store_dwordx2 v[16:17], v[12:13], off
	v_and_b32_sdwa v12, v10, v154 dst_sel:DWORD dst_unused:UNUSED_PAD src0_sel:WORD_1 src1_sel:DWORD
	v_and_b32_sdwa v13, v8, v154 dst_sel:DWORD dst_unused:UNUSED_PAD src0_sel:WORD_1 src1_sel:DWORD
	v_add3_u32 v8, v8, v13, s33
	v_add3_u32 v10, v10, v12, s33
	v_and_b32_sdwa v12, v11, v154 dst_sel:DWORD dst_unused:UNUSED_PAD src0_sel:WORD_1 src1_sel:DWORD
	v_and_b32_sdwa v13, v9, v154 dst_sel:DWORD dst_unused:UNUSED_PAD src0_sel:WORD_1 src1_sel:DWORD
	v_add3_u32 v11, v11, v12, s33
	v_add3_u32 v9, v9, v13, s33
	v_and_b32_e32 v11, 0xffff0000, v11
	v_and_b32_e32 v12, 0xffff0000, v9
	v_or_b32_sdwa v9, v11, v10 dst_sel:DWORD dst_unused:UNUSED_PAD src0_sel:DWORD src1_sel:WORD_1
	v_or_b32_sdwa v8, v12, v8 dst_sel:DWORD dst_unused:UNUSED_PAD src0_sel:DWORD src1_sel:WORD_1
	global_store_dwordx2 v[16:17], v[8:9], off offset:32
	v_and_b32_sdwa v8, v6, v154 dst_sel:DWORD dst_unused:UNUSED_PAD src0_sel:WORD_1 src1_sel:DWORD
	v_and_b32_sdwa v9, v4, v154 dst_sel:DWORD dst_unused:UNUSED_PAD src0_sel:WORD_1 src1_sel:DWORD
	v_add3_u32 v4, v4, v9, s33
	v_add3_u32 v6, v6, v8, s33
	v_and_b32_sdwa v8, v7, v154 dst_sel:DWORD dst_unused:UNUSED_PAD src0_sel:WORD_1 src1_sel:DWORD
	v_and_b32_sdwa v9, v5, v154 dst_sel:DWORD dst_unused:UNUSED_PAD src0_sel:WORD_1 src1_sel:DWORD
	v_add3_u32 v7, v7, v8, s33
	v_add3_u32 v5, v5, v9, s33
	v_and_b32_e32 v7, 0xffff0000, v7
	v_and_b32_e32 v8, 0xffff0000, v5
	v_or_b32_sdwa v5, v7, v6 dst_sel:DWORD dst_unused:UNUSED_PAD src0_sel:DWORD src1_sel:WORD_1
	v_or_b32_sdwa v4, v8, v4 dst_sel:DWORD dst_unused:UNUSED_PAD src0_sel:DWORD src1_sel:WORD_1
	global_store_dwordx2 v[16:17], v[4:5], off offset:64
	v_and_b32_sdwa v4, v2, v154 dst_sel:DWORD dst_unused:UNUSED_PAD src0_sel:WORD_1 src1_sel:DWORD
	v_and_b32_sdwa v5, v0, v154 dst_sel:DWORD dst_unused:UNUSED_PAD src0_sel:WORD_1 src1_sel:DWORD
	v_add3_u32 v0, v0, v5, s33
	v_add3_u32 v2, v2, v4, s33
	v_and_b32_sdwa v4, v3, v154 dst_sel:DWORD dst_unused:UNUSED_PAD src0_sel:WORD_1 src1_sel:DWORD
	v_and_b32_sdwa v5, v1, v154 dst_sel:DWORD dst_unused:UNUSED_PAD src0_sel:WORD_1 src1_sel:DWORD
	v_add3_u32 v3, v3, v4, s33
	v_add3_u32 v1, v1, v5, s33
	v_and_b32_e32 v3, 0xffff0000, v3
	v_and_b32_e32 v4, 0xffff0000, v1
	v_or_b32_sdwa v1, v3, v2 dst_sel:DWORD dst_unused:UNUSED_PAD src0_sel:DWORD src1_sel:WORD_1
	v_or_b32_sdwa v0, v4, v0 dst_sel:DWORD dst_unused:UNUSED_PAD src0_sel:DWORD src1_sel:WORD_1
	global_store_dwordx2 v[16:17], v[0:1], off offset:96
